# stick-breaking units 256..511 handed out dynamically from one counter, q-block descending (short q-block 0/1 units free their workgroups for more), on top of per-XCD dynamic differential units
# speedup vs baseline: 1.0050x; 1.0050x over previous
.LBB0_584:
	s_ashr_i32 s4, s66, 31
	v_lshrrev_b32_e32 v0, 4, v149
	s_add_u32 s5, s38, s66
	v_or_b32_e32 v98, s5, v0
	v_mov_b64_e32 v[66:67], s[12:13]
	s_addc_u32 s6, s39, s4
	v_mad_u64_u32 v[66:67], s[4:5], v98, s44, v[66:67]
	v_mad_i32_i24 v67, s6, v196, v67
	s_lshl_b32 s8, s67, 1
	v_lshl_add_u64 v[66:67], v[66:67], 0, s[8:9]
	v_mov_b32_e32 v149, v1
	v_lshl_add_u64 v[66:67], v[66:67], 0, v[148:149]
	v_add_co_u32_e32 v68, vcc, s50, v66
	s_mulk_i32 s64, 0x2200
	s_nop 0
	v_addc_co_u32_e32 v69, vcc, 0, v67, vcc
	v_add_co_u32_e32 v70, vcc, s51, v66
	s_add_i32 s4, s64, 0
	s_nop 0
	v_addc_co_u32_e32 v71, vcc, 0, v67, vcc
	global_load_dwordx4 v[90:93], v[68:69], off
	global_load_dwordx4 v[94:97], v[70:71], off
	v_add_co_u32_e32 v68, vcc, s52, v66
	v_add3_u32 v100, s4, v197, v151
	s_nop 0
	v_addc_co_u32_e32 v69, vcc, 0, v67, vcc
	v_add_co_u32_e32 v70, vcc, s53, v66
	v_cvt_pk_bf16_f32 v50, v50, v51
	s_nop 0
	v_addc_co_u32_e32 v71, vcc, 0, v67, vcc
	global_load_dwordx4 v[86:89], v[68:69], off
	global_load_dwordx4 v[82:85], v[70:71], off
	v_add_co_u32_e32 v68, vcc, s54, v66
	v_cvt_pk_bf16_f32 v51, v52, v53
	s_nop 0
	v_addc_co_u32_e32 v69, vcc, 0, v67, vcc
	v_add_co_u32_e32 v70, vcc, s55, v66
	v_cvt_pk_bf16_f32 v52, v54, v55
	s_nop 0
	v_addc_co_u32_e32 v71, vcc, 0, v67, vcc
	global_load_dwordx4 v[78:81], v[68:69], off
	global_load_dwordx4 v[74:77], v[70:71], off
	v_add_co_u32_e32 v68, vcc, s56, v66
	v_cvt_pk_bf16_f32 v53, v56, v57
	s_nop 0
	v_addc_co_u32_e32 v69, vcc, 0, v67, vcc
	v_add_co_u32_e32 v66, vcc, s57, v66
	v_cvt_pk_bf16_f32 v34, v34, v35
	s_nop 0
	v_addc_co_u32_e32 v67, vcc, 0, v67, vcc
	global_load_dwordx4 v[70:73], v[68:69], off
	s_nop 0
	global_load_dwordx4 v[66:69], v[66:67], off
	v_cvt_pk_bf16_f32 v35, v36, v37
	v_cvt_pk_bf16_f32 v36, v38, v39
	v_cvt_pk_bf16_f32 v37, v40, v41
	v_cvt_pk_bf16_f32 v18, v18, v19
	v_cvt_pk_bf16_f32 v19, v20, v21
	v_cvt_pk_bf16_f32 v20, v22, v23
	v_cvt_pk_bf16_f32 v21, v24, v25
	v_cvt_pk_bf16_f32 v2, v2, v3
	v_cvt_pk_bf16_f32 v3, v4, v5
	v_cvt_pk_bf16_f32 v4, v6, v7
	v_cvt_pk_bf16_f32 v5, v8, v9
	ds_write2_b64 v100, v[50:51], v[52:53] offset1:2
	v_cvt_pk_bf16_f32 v50, v58, v59
	v_cvt_pk_bf16_f32 v51, v60, v61
	v_cvt_pk_bf16_f32 v52, v62, v63
	v_cvt_pk_bf16_f32 v53, v64, v65
	ds_write2_b64 v100, v[34:35], v[36:37] offset0:8 offset1:10
	v_cvt_pk_bf16_f32 v34, v42, v43
	v_cvt_pk_bf16_f32 v35, v44, v45
	v_cvt_pk_bf16_f32 v36, v46, v47
	v_cvt_pk_bf16_f32 v37, v48, v49
	ds_write2_b64 v100, v[18:19], v[20:21] offset0:16 offset1:18
	v_cvt_pk_bf16_f32 v18, v26, v27
	v_cvt_pk_bf16_f32 v19, v28, v29
	v_cvt_pk_bf16_f32 v20, v30, v31
	v_cvt_pk_bf16_f32 v21, v32, v33
	ds_write2_b64 v100, v[2:3], v[4:5] offset0:24 offset1:26
	v_cvt_pk_bf16_f32 v2, v10, v11
	v_cvt_pk_bf16_f32 v3, v12, v13
	v_cvt_pk_bf16_f32 v4, v14, v15
	v_cvt_pk_bf16_f32 v5, v16, v17
	ds_write2_b64 v100, v[50:51], v[52:53] offset0:4 offset1:6
	ds_write2_b64 v100, v[34:35], v[36:37] offset0:12 offset1:14
	ds_write2_b64 v100, v[18:19], v[20:21] offset0:20 offset1:22
	ds_write2_b64 v100, v[2:3], v[4:5] offset0:28 offset1:30
	v_mul_u32_u24_e32 v0, 0x110, v0
	s_waitcnt lgkmcnt(0)
	v_add3_u32 v0, s4, v148, v0
	ds_read_b128 v[4:7], v0
	ds_read_b128 v[8:11], v0 offset:1088
	v_mov_b32_e32 v99, s6
	v_lshlrev_b64 v[2:3], 12, v[98:99]
	v_lshl_add_u64 v[2:3], s[10:11], 0, v[2:3]
	s_waitcnt lgkmcnt(1)
	v_lshlrev_b32_e32 v12, 16, v4
	v_and_b32_e32 v13, 0xffff0000, v4
	s_waitcnt vmcnt(7)
	v_lshlrev_b32_e32 v14, 16, v90
	v_and_b32_e32 v15, 0xffff0000, v90
	v_pk_mul_f32 v[12:13], v[14:15], v[12:13]
	v_lshlrev_b32_e32 v14, 16, v91
	v_cvt_pk_bf16_f32 v4, v12, v13
	v_lshlrev_b32_e32 v12, 16, v5
	v_and_b32_e32 v13, 0xffff0000, v5
	v_and_b32_e32 v15, 0xffff0000, v91
	v_pk_mul_f32 v[12:13], v[14:15], v[12:13]
	v_lshlrev_b32_e32 v14, 16, v92
	v_cvt_pk_bf16_f32 v5, v12, v13
	v_lshlrev_b32_e32 v12, 16, v6
	v_and_b32_e32 v13, 0xffff0000, v6
	v_and_b32_e32 v15, 0xffff0000, v92
	v_pk_mul_f32 v[12:13], v[14:15], v[12:13]
	v_lshlrev_b32_e32 v14, 16, v93
	v_cvt_pk_bf16_f32 v6, v12, v13
	v_lshlrev_b32_e32 v12, 16, v7
	v_and_b32_e32 v13, 0xffff0000, v7
	v_and_b32_e32 v15, 0xffff0000, v93
	v_lshl_add_u64 v[2:3], v[2:3], 0, s[8:9]
	v_pk_mul_f32 v[12:13], v[14:15], v[12:13]
	v_lshl_add_u64 v[2:3], v[2:3], 0, v[148:149]
	v_cvt_pk_bf16_f32 v7, v12, v13
	global_store_dwordx4 v[2:3], v[4:7], off
	v_add_co_u32_e32 v12, vcc, s58, v2
	s_waitcnt lgkmcnt(0)
	v_lshlrev_b32_e32 v4, 16, v8
	v_and_b32_e32 v5, 0xffff0000, v8
	s_waitcnt vmcnt(7)
	v_lshlrev_b32_e32 v6, 16, v94
	v_and_b32_e32 v7, 0xffff0000, v94
	v_pk_mul_f32 v[4:5], v[6:7], v[4:5]
	v_lshlrev_b32_e32 v6, 16, v9
	v_and_b32_e32 v7, 0xffff0000, v9
	v_lshlrev_b32_e32 v8, 16, v95
	v_and_b32_e32 v9, 0xffff0000, v95
	v_pk_mul_f32 v[6:7], v[8:9], v[6:7]
	v_cvt_pk_bf16_f32 v4, v4, v5
	v_cvt_pk_bf16_f32 v5, v6, v7
	v_lshlrev_b32_e32 v6, 16, v10
	v_and_b32_e32 v7, 0xffff0000, v10
	v_lshlrev_b32_e32 v8, 16, v96
	v_and_b32_e32 v9, 0xffff0000, v96
	v_pk_mul_f32 v[6:7], v[8:9], v[6:7]
	v_lshlrev_b32_e32 v8, 16, v11
	v_and_b32_e32 v9, 0xffff0000, v11
	v_lshlrev_b32_e32 v10, 16, v97
	v_and_b32_e32 v11, 0xffff0000, v97
	v_pk_mul_f32 v[8:9], v[10:11], v[8:9]
	v_cvt_pk_bf16_f32 v6, v6, v7
	v_cvt_pk_bf16_f32 v7, v8, v9
	ds_read_b128 v[8:11], v0 offset:2176
	v_addc_co_u32_e32 v13, vcc, 0, v3, vcc
	global_store_dwordx4 v[12:13], v[4:7], off
	ds_read_b128 v[4:7], v0 offset:3264
	s_waitcnt lgkmcnt(1)
	v_lshlrev_b32_e32 v12, 16, v8
	v_and_b32_e32 v13, 0xffff0000, v8
	s_waitcnt vmcnt(7)
	v_lshlrev_b32_e32 v14, 16, v86
	v_and_b32_e32 v15, 0xffff0000, v86
	v_pk_mul_f32 v[12:13], v[14:15], v[12:13]
	v_lshlrev_b32_e32 v14, 16, v87
	v_cvt_pk_bf16_f32 v8, v12, v13
	v_lshlrev_b32_e32 v12, 16, v9
	v_and_b32_e32 v13, 0xffff0000, v9
	v_and_b32_e32 v15, 0xffff0000, v87
	v_pk_mul_f32 v[12:13], v[14:15], v[12:13]
	v_lshlrev_b32_e32 v14, 16, v88
	v_cvt_pk_bf16_f32 v9, v12, v13
	v_lshlrev_b32_e32 v12, 16, v10
	v_and_b32_e32 v13, 0xffff0000, v10
	v_and_b32_e32 v15, 0xffff0000, v88
	v_pk_mul_f32 v[12:13], v[14:15], v[12:13]
	v_lshlrev_b32_e32 v14, 16, v89
	v_cvt_pk_bf16_f32 v10, v12, v13
	v_lshlrev_b32_e32 v12, 16, v11
	v_and_b32_e32 v13, 0xffff0000, v11
	v_and_b32_e32 v15, 0xffff0000, v89
	v_pk_mul_f32 v[12:13], v[14:15], v[12:13]
	s_waitcnt vmcnt(5)
	v_lshlrev_b32_e32 v14, 16, v78
	v_cvt_pk_bf16_f32 v11, v12, v13
	v_add_co_u32_e32 v12, vcc, s59, v2
	v_and_b32_e32 v15, 0xffff0000, v78
	s_nop 0
	v_addc_co_u32_e32 v13, vcc, 0, v3, vcc
	global_store_dwordx4 v[12:13], v[8:11], off
	v_add_co_u32_e32 v12, vcc, s45, v2
	s_waitcnt lgkmcnt(0)
	v_lshlrev_b32_e32 v8, 16, v4
	v_and_b32_e32 v9, 0xffff0000, v4
	v_lshlrev_b32_e32 v10, 16, v82
	v_and_b32_e32 v11, 0xffff0000, v82
	v_pk_mul_f32 v[8:9], v[10:11], v[8:9]
	v_lshlrev_b32_e32 v10, 16, v83
	v_cvt_pk_bf16_f32 v4, v8, v9
	v_lshlrev_b32_e32 v8, 16, v5
	v_and_b32_e32 v9, 0xffff0000, v5
	v_and_b32_e32 v11, 0xffff0000, v83
	v_pk_mul_f32 v[8:9], v[10:11], v[8:9]
	v_lshlrev_b32_e32 v10, 16, v84
	v_cvt_pk_bf16_f32 v5, v8, v9
	v_lshlrev_b32_e32 v8, 16, v6
	v_and_b32_e32 v9, 0xffff0000, v6
	v_and_b32_e32 v11, 0xffff0000, v84
	v_pk_mul_f32 v[8:9], v[10:11], v[8:9]
	v_lshlrev_b32_e32 v10, 16, v85
	v_cvt_pk_bf16_f32 v6, v8, v9
	v_lshlrev_b32_e32 v8, 16, v7
	v_and_b32_e32 v9, 0xffff0000, v7
	v_and_b32_e32 v11, 0xffff0000, v85
	v_pk_mul_f32 v[8:9], v[10:11], v[8:9]
	v_addc_co_u32_e32 v13, vcc, 0, v3, vcc
	v_cvt_pk_bf16_f32 v7, v8, v9
	ds_read_b128 v[8:11], v0 offset:4352
	global_store_dwordx4 v[12:13], v[4:7], off
	ds_read_b128 v[4:7], v0 offset:5440
	s_add_i32 s3, s3, s24
	s_add_i32 s63, s63, s24
	s_waitcnt lgkmcnt(1)
	v_lshlrev_b32_e32 v12, 16, v8
	v_and_b32_e32 v13, 0xffff0000, v8
	v_pk_mul_f32 v[12:13], v[14:15], v[12:13]
	v_lshlrev_b32_e32 v14, 16, v79
	v_cvt_pk_bf16_f32 v8, v12, v13
	v_lshlrev_b32_e32 v12, 16, v9
	v_and_b32_e32 v13, 0xffff0000, v9
	v_and_b32_e32 v15, 0xffff0000, v79
	v_pk_mul_f32 v[12:13], v[14:15], v[12:13]
	v_lshlrev_b32_e32 v14, 16, v80
	v_cvt_pk_bf16_f32 v9, v12, v13
	v_lshlrev_b32_e32 v12, 16, v10
	v_and_b32_e32 v13, 0xffff0000, v10
	v_and_b32_e32 v15, 0xffff0000, v80
	v_pk_mul_f32 v[12:13], v[14:15], v[12:13]
	v_lshlrev_b32_e32 v14, 16, v81
	v_cvt_pk_bf16_f32 v10, v12, v13
	v_lshlrev_b32_e32 v12, 16, v11
	v_and_b32_e32 v13, 0xffff0000, v11
	v_and_b32_e32 v15, 0xffff0000, v81
	v_pk_mul_f32 v[12:13], v[14:15], v[12:13]
	s_waitcnt vmcnt(5)
	v_lshlrev_b32_e32 v14, 16, v70
	v_cvt_pk_bf16_f32 v11, v12, v13
	v_add_co_u32_e32 v12, vcc, s60, v2
	v_and_b32_e32 v15, 0xffff0000, v70
	s_nop 0
	v_addc_co_u32_e32 v13, vcc, 0, v3, vcc
	global_store_dwordx4 v[12:13], v[8:11], off
	v_add_co_u32_e32 v12, vcc, s61, v2
	s_waitcnt lgkmcnt(0)
	v_lshlrev_b32_e32 v8, 16, v4
	v_and_b32_e32 v9, 0xffff0000, v4
	v_lshlrev_b32_e32 v10, 16, v74
	v_and_b32_e32 v11, 0xffff0000, v74
	v_pk_mul_f32 v[8:9], v[10:11], v[8:9]
	v_lshlrev_b32_e32 v10, 16, v75
	v_cvt_pk_bf16_f32 v4, v8, v9
	v_lshlrev_b32_e32 v8, 16, v5
	v_and_b32_e32 v9, 0xffff0000, v5
	v_and_b32_e32 v11, 0xffff0000, v75
	v_pk_mul_f32 v[8:9], v[10:11], v[8:9]
	v_lshlrev_b32_e32 v10, 16, v76
	v_cvt_pk_bf16_f32 v5, v8, v9
	v_lshlrev_b32_e32 v8, 16, v6
	v_and_b32_e32 v9, 0xffff0000, v6
	v_and_b32_e32 v11, 0xffff0000, v76
	v_pk_mul_f32 v[8:9], v[10:11], v[8:9]
	v_lshlrev_b32_e32 v10, 16, v77
	v_cvt_pk_bf16_f32 v6, v8, v9
	v_lshlrev_b32_e32 v8, 16, v7
	v_and_b32_e32 v9, 0xffff0000, v7
	v_and_b32_e32 v11, 0xffff0000, v77
	v_pk_mul_f32 v[8:9], v[10:11], v[8:9]
	v_addc_co_u32_e32 v13, vcc, 0, v3, vcc
	v_cvt_pk_bf16_f32 v7, v8, v9
	ds_read_b128 v[8:11], v0 offset:6528
	global_store_dwordx4 v[12:13], v[4:7], off
	ds_read_b128 v[4:7], v0 offset:7616
	s_cmpk_gt_i32 s3, 0x1ff
	s_waitcnt lgkmcnt(1)
	v_lshlrev_b32_e32 v12, 16, v8
	v_and_b32_e32 v13, 0xffff0000, v8
	v_pk_mul_f32 v[12:13], v[14:15], v[12:13]
	v_lshlrev_b32_e32 v14, 16, v71
	v_cvt_pk_bf16_f32 v8, v12, v13
	v_lshlrev_b32_e32 v12, 16, v9
	v_and_b32_e32 v13, 0xffff0000, v9
	v_and_b32_e32 v15, 0xffff0000, v71
	v_pk_mul_f32 v[12:13], v[14:15], v[12:13]
	v_lshlrev_b32_e32 v14, 16, v72
	v_cvt_pk_bf16_f32 v9, v12, v13
	v_lshlrev_b32_e32 v12, 16, v10
	v_and_b32_e32 v13, 0xffff0000, v10
	v_and_b32_e32 v15, 0xffff0000, v72
	v_pk_mul_f32 v[12:13], v[14:15], v[12:13]
	v_lshlrev_b32_e32 v14, 16, v73
	v_cvt_pk_bf16_f32 v10, v12, v13
	v_lshlrev_b32_e32 v12, 16, v11
	v_and_b32_e32 v13, 0xffff0000, v11
	v_and_b32_e32 v15, 0xffff0000, v73
	v_pk_mul_f32 v[12:13], v[14:15], v[12:13]
	s_nop 0
	v_cvt_pk_bf16_f32 v11, v12, v13
	v_add_co_u32_e32 v12, vcc, s62, v2
	s_nop 1
	v_addc_co_u32_e32 v13, vcc, 0, v3, vcc
	global_store_dwordx4 v[12:13], v[8:11], off
	v_add_co_u32_e32 v2, vcc, 0x1c000, v2
	s_waitcnt lgkmcnt(0)
	v_lshlrev_b32_e32 v8, 16, v4
	v_and_b32_e32 v9, 0xffff0000, v4
	s_waitcnt vmcnt(7)
	v_lshlrev_b32_e32 v10, 16, v66
	v_and_b32_e32 v11, 0xffff0000, v66
	v_pk_mul_f32 v[8:9], v[10:11], v[8:9]
	v_lshlrev_b32_e32 v10, 16, v67
	v_cvt_pk_bf16_f32 v4, v8, v9
	v_lshlrev_b32_e32 v8, 16, v5
	v_and_b32_e32 v9, 0xffff0000, v5
	v_and_b32_e32 v11, 0xffff0000, v67
	v_pk_mul_f32 v[8:9], v[10:11], v[8:9]
	v_lshlrev_b32_e32 v10, 16, v68
	v_cvt_pk_bf16_f32 v5, v8, v9
	v_lshlrev_b32_e32 v8, 16, v6
	v_and_b32_e32 v9, 0xffff0000, v6
	v_and_b32_e32 v11, 0xffff0000, v68
	v_pk_mul_f32 v[8:9], v[10:11], v[8:9]
	v_lshlrev_b32_e32 v10, 16, v69
	v_cvt_pk_bf16_f32 v6, v8, v9
	v_lshlrev_b32_e32 v8, 16, v7
	v_and_b32_e32 v9, 0xffff0000, v7
	v_and_b32_e32 v11, 0xffff0000, v69
	v_pk_mul_f32 v[8:9], v[10:11], v[8:9]
	v_addc_co_u32_e32 v3, vcc, 0, v3, vcc
	v_cvt_pk_bf16_f32 v7, v8, v9
	global_store_dwordx4 v[2:3], v[4:7], off
	s_cmpk_lg_u32 s24, 0x100
	s_cbranch_scc1 .Lsq_static
	v_readfirstlane_b32 s96, v225
	v_mov_b32_e32 v236, 0x20400
	s_nop 3
	s_cmp_ge_u32 s96, 64
	s_cbranch_scc1 .Lsq_nw
	v_readfirstlane_b32 s98, v233
	s_nop 3
	v_mov_b32_e32 v237, s98
	ds_write_b32 v236, v237
	s_waitcnt lgkmcnt(0)
.Lsq_nw:
	s_barrier
	ds_read_b32 v237, v236
	s_waitcnt lgkmcnt(0)
	v_readfirstlane_b32 s97, v237
	s_nop 3
	s_cmpk_gt_u32 s97, 0xff
	s_cbranch_scc1 .LBB0_601
	s_bfe_u32 s96, s97, 0x20003
	s_add_i32 s96, s96, 4
	s_lshl_b32 s96, s96, 6
	s_and_b32 s3, s97, 7
	s_lshl_b32 s3, s3, 3
	s_or_b32 s3, s3, s96
	s_lshr_b32 s96, s97, 5
	s_sub_i32 s96, 7, s96
	s_or_b32 s3, s3, s96
	s_mov_b32 s63, s3
	s_branch .LBB0_585

.LBB0_585:
	s_and_b32 s4, s63, 7
	s_lshl_b32 s5, s4, 2
	v_mov_b32_e32 v6, v225
	s_or_b32 s71, s5, 2
	s_and_b32 s42, s3, 7
	v_readfirstlane_b32 s5, v6
	s_ashr_i32 s64, s5, 6
	s_cmpk_lg_u32 s24, 0x100
	s_cbranch_scc1 .Lsq_noat
	s_cmp_lg_u32 s64, 0
	s_cbranch_scc1 .Lsq_noat
	s_add_u32 s94, s22, 0x83620
	s_addc_u32 s95, s23, 0
	s_mov_b64 s[92:93], exec
	s_mov_b64 exec, 1
	v_mov_b32_e32 v231, 0
	v_mov_b32_e32 v232, 1
	global_atomic_add v233, v231, v232, s[94:95] sc0
	s_mov_b64 exec, s[92:93]
.Lsq_noat:
	s_lshl_b32 s65, s4, 8
	s_ashr_i32 s4, s3, 6
	s_lshl_b32 s5, s42, 8
	s_lshl_b32 s66, s64, 5
	s_add_i32 s66, s66, s5
	s_ashr_i32 s5, s4, 31
	s_bfe_u32 s8, s3, 0x30003
	v_and_b32_e32 v7, 31, v6
	s_lshl_b64 s[38:39], s[4:5], 11
	s_lshl_b32 s4, s4, 3
	s_waitcnt vmcnt(2)
	v_or_b32_e32 v150, s66, v7
	s_or_b32 s4, s4, s8
	s_ashr_i32 s5, s4, 31
	v_ashrrev_i32_e32 v151, 31, v150
	s_lshl_b64 s[4:5], s[4:5], 19
	v_lshl_add_u64 v[2:3], s[38:39], 0, v[150:151]
	s_add_u32 s6, s14, s4
	v_mad_u64_u32 v[4:5], s[40:41], v2, s44, v[146:147]
	v_bfe_u32 v8, v6, 5, 1
	s_addc_u32 s7, s15, s5
	v_mad_i32_i24 v5, v3, s44, v5
	s_lshl_b32 s67, s8, 7
	s_lshl_b32 s8, s8, 8
	v_lshl_add_u64 v[2:3], v[4:5], 0, s[8:9]
	v_lshlrev_b32_e32 v0, 4, v8
	v_lshl_add_u64 v[2:3], v[2:3], 0, v[0:1]
	global_load_dwordx4 v[98:101], v[2:3], off
	global_load_dwordx4 v[102:105], v[2:3], off offset:32
	global_load_dwordx4 v[106:109], v[2:3], off offset:64
	global_load_dwordx4 v[110:113], v[2:3], off offset:96
	global_load_dwordx4 v[114:117], v[2:3], off offset:128
	global_load_dwordx4 v[118:121], v[2:3], off offset:160
	global_load_dwordx4 v[122:125], v[2:3], off offset:192
	global_load_dwordx4 v[126:129], v[2:3], off offset:224
	v_lshlrev_b32_e32 v2, 3, v6
	s_add_u32 s4, s81, s4
	v_ashrrev_i32_e32 v3, 31, v2
	s_addc_u32 s5, s82, s5
	v_lshlrev_b64 v[2:3], 1, v[2:3]
	v_mov_b32_e32 v228, v2
	v_add_u32_e32 v229, 0x2000, v2
	s_waitcnt vmcnt(9)
	s_mov_b64 s[90:91], s[4:5]
	v_lshl_add_u64 v[154:155], s[4:5], 0, v[2:3]
	s_lshl_b32 s4, s42, 16
	s_mov_b64 s[88:89], s[6:7]
	v_lshl_add_u64 v[152:153], s[6:7], 0, v[2:3]
	s_or_b32 s8, s4, 0xc000
	v_lshl_add_u64 v[2:3], v[152:153], 0, s[8:9]
	s_barrier
	v_lshl_add_u64 v[4:5], v[154:155], 0, s[8:9]
	global_load_dwordx4 v[130:133], v[2:3], off
	global_load_dwordx4 v[134:137], v[4:5], off
	v_add_co_u32_e32 v2, vcc, s46, v2
	v_and_b32_e32 v149, 63, v6
	s_nop 0
	v_addc_co_u32_e32 v3, vcc, 0, v3, vcc
	v_add_co_u32_e32 v4, vcc, s46, v4
	v_mul_u32_u24_e32 v197, 0x110, v7
	s_nop 0
	v_addc_co_u32_e32 v5, vcc, 0, v5, vcc
	global_load_dwordx4 v[138:141], v[2:3], off
	global_load_dwordx4 v[142:145], v[4:5], off
	v_lshlrev_b32_e32 v2, 4, v6
	v_lshrrev_b32_e32 v3, 3, v6
	v_lshrrev_b32_e32 v4, 4, v6
	v_and_b32_e32 v148, 0xf0, v2
	v_and_b32_e32 v2, 0x70, v2
	s_waitcnt vmcnt(12)
	v_mad_u64_u32 v[156:157], s[4:5], v4, s47, v[148:149]
	v_mad_u64_u32 v[158:159], s[4:5], v3, s48, v[2:3]
	v_lshlrev_b32_e32 v5, 7, v7
	v_add3_u32 v157, 0, v197, v0
	v_add_u32_e32 v0, 0, v156
	v_add_u32_e32 v2, 0, v158
	v_mov_b32_e32 v14, v1
	v_mov_b32_e32 v15, v1
	v_lshlrev_b32_e32 v151, 3, v8
	s_lshl_b32 s4, s64, 2
	v_lshlrev_b32_e32 v159, 2, v8
	v_sub_u32_e32 v198, v157, v5
	v_mov_b32_e32 v3, v1
	v_mov_b32_e32 v4, v1
	v_mov_b32_e32 v5, v1
	v_mov_b32_e32 v6, v1
	v_mov_b32_e32 v7, v1
	v_mov_b32_e32 v8, v1
	v_mov_b32_e32 v9, v1
	v_mov_b32_e32 v10, v1
	v_mov_b32_e32 v11, v1
	v_mov_b32_e32 v12, v1
	v_mov_b32_e32 v13, v1
	s_add_i32 s69, s4, 0
	v_cmp_eq_u32_e64 s[6:7], 0, v149
	s_or_b32 s68, s66, 30
	s_add_i32 s69, s69, 0x11800
	v_cmp_gt_u32_e64 s[4:5], 32, v149
	s_mov_b64 s[42:43], 0
	s_mov_b32 s70, s9
	s_mov_b32 s8, s71
	s_mov_b32 s71, s9
	s_waitcnt vmcnt(3)
	ds_write_b128 v0, v[130:133]
	s_waitcnt vmcnt(2)
	ds_write_b128 v2, v[134:137] offset:17408
	s_waitcnt vmcnt(1)
	ds_write_b128 v0, v[138:141] offset:8704
	s_waitcnt vmcnt(0)
	ds_write_b128 v2, v[142:145] offset:26624
	v_mov_b32_e32 v0, v1
	v_mov_b32_e32 v2, v1
	v_mov_b64_e32 v[64:65], v[14:15]
	v_mov_b64_e32 v[48:49], v[14:15]
	v_mov_b64_e32 v[32:33], v[14:15]
	v_mov_b64_e32 v[62:63], v[12:13]
	v_mov_b64_e32 v[60:61], v[10:11]
	v_mov_b64_e32 v[58:59], v[8:9]
	v_mov_b64_e32 v[56:57], v[6:7]
	v_mov_b64_e32 v[54:55], v[4:5]
	v_mov_b64_e32 v[52:53], v[2:3]
	v_mov_b64_e32 v[50:51], v[0:1]
	v_mov_b64_e32 v[46:47], v[12:13]
	v_mov_b64_e32 v[44:45], v[10:11]
	v_mov_b64_e32 v[42:43], v[8:9]
	v_mov_b64_e32 v[40:41], v[6:7]
	v_mov_b64_e32 v[38:39], v[4:5]
	v_mov_b64_e32 v[36:37], v[2:3]
	v_mov_b64_e32 v[34:35], v[0:1]
	v_mov_b64_e32 v[30:31], v[12:13]
	v_mov_b64_e32 v[28:29], v[10:11]
	v_mov_b64_e32 v[26:27], v[8:9]
	v_mov_b64_e32 v[24:25], v[6:7]
	v_mov_b64_e32 v[22:23], v[4:5]
	v_mov_b64_e32 v[20:21], v[2:3]
	v_mov_b64_e32 v[18:19], v[0:1]
	v_mov_b64_e32 v[16:17], v[14:15]
	v_mov_b64_e32 v[14:15], v[12:13]
	v_mov_b64_e32 v[12:13], v[10:11]
	v_mov_b64_e32 v[10:11], v[8:9]
	v_mov_b64_e32 v[8:9], v[6:7]
	v_mov_b64_e32 v[6:7], v[4:5]
	v_mov_b64_e32 v[4:5], v[2:3]
	v_mov_b64_e32 v[2:3], v[0:1]
	v_mov_b32_e32 v0, 0
	s_waitcnt lgkmcnt(0)
	s_barrier
	s_branch .LBB0_587
	s_nop 0
	s_nop 0
	s_nop 0
	s_nop 0
	s_nop 0
	s_nop 0
	s_nop 0
	s_nop 0
	s_nop 0
	s_nop 0
	s_nop 0
	s_nop 0
	s_nop 0
	s_nop 0
	s_nop 0
	s_nop 0
	s_nop 0
	s_nop 0
	s_nop 0
	s_nop 0
	s_nop 0
	s_nop 0
	s_nop 0
	s_nop 0
	s_nop 0
	s_nop 0
	s_nop 0
	s_nop 0
	s_nop 0
	s_nop 0
	s_nop 0
	s_nop 0
	s_nop 0
	s_nop 0
	s_nop 0
	s_nop 0
	s_nop 0
	s_nop 0
	s_nop 0
	s_nop 0
